# grid barriers 2..7 rewritten by hand: same XCD-hierarchical counters, every workgroup polls the top generation word directly (no per-XCD relay), arrival tests use the known barrier index
# speedup vs baseline: 1.2713x; 1.0003x over previous
.LBB0_242:
	s_waitcnt vmcnt(0)
	s_waitcnt vmcnt(0)
	s_barrier
	s_and_saveexec_b64 s[0:1], s[60:61]
	s_cbranch_execz .LBB0_294
	v_mov_b32_e32 v0, 0x27d60
	ds_read_b32 v1, v0
	ds_read_b32 v2, v0 offset:4
	s_mov_b32 s3, s65
	s_add_u32 s4, s86, 0x4000
	s_addc_u32 s5, s87, 0
	v_mov_b32_e32 v4, 1
	s_lshl_b32 s3, s3, 8
	s_add_i32 s3, s3, 0x1400
	v_mov_b32_e32 v3, s3
	v_mov_b32_e32 v6, 0x3500
	s_waitcnt lgkmcnt(0)
	global_atomic_add v5, v3, v4, s[4:5] sc0
	v_readfirstlane_b32 s6, v1
	v_readfirstlane_b32 s7, v2
	s_mul_i32 s11, s6, 2
	s_waitcnt vmcnt(0)
	v_readfirstlane_b32 s10, v5
	s_add_i32 s10, s10, 1
	s_cmp_lg_u32 s10, s11
	s_cbranch_scc1 .Lgb1_poll
	buffer_wbl2 sc1
	s_waitcnt vmcnt(0)
	v_mov_b32_e32 v3, 0x3400
	global_atomic_add v5, v3, v4, s[4:5] sc0
	s_mul_i32 s11, s7, 2
	s_waitcnt vmcnt(0)
	v_readfirstlane_b32 s10, v5
	s_add_i32 s10, s10, 1
	s_cmp_lg_u32 s10, s11
	s_cbranch_scc1 .Lgb1_poll
	global_atomic_add v6, v4, s[4:5]
	s_branch .Lgb1_acq
.Lgb1_poll:
	s_mov_b32 s12, 0
.Lgb1_spin:
	s_sleep 1
	global_load_dword v7, v6, s[4:5] sc1
	s_add_i32 s12, s12, 1
	s_waitcnt vmcnt(0)
	v_readfirstlane_b32 s13, v7
	s_cmp_lg_u32 s13, 1
	s_cbranch_scc1 .Lgb1_acq
	s_cmp_lt_u32 s12, 0x10000
	s_cbranch_scc1 .Lgb1_spin
.Lgb1_acq:
	buffer_inv sc1
.LBB0_294:
	s_or_b64 exec, exec, s[0:1]
	v_writelane_b32 v244, s65, 30
	s_waitcnt lgkmcnt(0)
	v_mov_b32_e32 v0, v214
	v_readlane_b32 s0, v244, 0
	s_mov_b32 s56, 0
	s_cmpk_gt_i32 s0, 0x8ff
	s_mov_b32 s54, 0
	s_barrier
	s_cbranch_scc1 .LBB0_296
	s_abs_i32 s0, s66
	v_cvt_f32_u32_e32 v1, s0
	v_readlane_b32 s1, v244, 0
	s_sub_i32 s1, s66, s1
	s_add_i32 s3, s1, 0x8ff
	v_rcp_iflag_f32_e32 v1, v1
	s_sub_i32 s1, 0xfffff701, s1
	s_xor_b32 s5, s3, s66
	s_sub_i32 s4, 0, s0
	v_mul_f32_e32 v1, 0x4f7ffffe, v1
	v_cvt_u32_f32_e32 v1, v1
	s_max_i32 s1, s3, s1
	s_ashr_i32 s3, s5, 31
	v_readfirstlane_b32 s5, v1
	s_mul_i32 s4, s4, s5
	s_mul_hi_u32 s4, s5, s4
	s_add_i32 s5, s5, s4
	s_mul_hi_u32 s4, s1, s5
	s_mul_i32 s5, s4, s0
	s_sub_i32 s1, s1, s5
	s_add_i32 s6, s4, 1
	s_sub_i32 s5, s1, s0
	s_cmp_ge_u32 s1, s0
	s_cselect_b32 s4, s6, s4
	s_cselect_b32 s1, s5, s1
	s_add_i32 s5, s4, 1
	s_cmp_ge_u32 s1, s0
	s_cselect_b32 s0, s5, s4
	s_xor_b32 s0, s0, s3
	s_sub_i32 s0, s0, s3
	s_mul_i32 s54, s0, 6

.LBB0_336:
	s_barrier
	s_waitcnt vmcnt(0)
	s_barrier
	s_and_saveexec_b64 s[0:1], s[70:71]
	s_cbranch_execz .LBB0_388
	v_mov_b32_e32 v0, 0x27d60
	ds_read_b32 v1, v0
	ds_read_b32 v2, v0 offset:4
	v_readlane_b32 s3, v244, 30
	s_add_u32 s4, s74, 0x4000
	s_addc_u32 s5, s75, 0
	v_mov_b32_e32 v4, 1
	s_lshl_b32 s3, s3, 8
	s_add_i32 s3, s3, 0x1400
	v_mov_b32_e32 v3, s3
	v_mov_b32_e32 v6, 0x3500
	s_waitcnt lgkmcnt(0)
	global_atomic_add v5, v3, v4, s[4:5] sc0
	v_readfirstlane_b32 s6, v1
	v_readfirstlane_b32 s7, v2
	s_mul_i32 s11, s6, 3
	s_waitcnt vmcnt(0)
	v_readfirstlane_b32 s10, v5
	s_add_i32 s10, s10, 1
	s_cmp_lg_u32 s10, s11
	s_cbranch_scc1 .Lgb2_poll
	buffer_wbl2 sc1
	s_waitcnt vmcnt(0)
	v_mov_b32_e32 v3, 0x3400
	global_atomic_add v5, v3, v4, s[4:5] sc0
	s_mul_i32 s11, s7, 3
	s_waitcnt vmcnt(0)
	v_readfirstlane_b32 s10, v5
	s_add_i32 s10, s10, 1
	s_cmp_lg_u32 s10, s11
	s_cbranch_scc1 .Lgb2_poll
	global_atomic_add v6, v4, s[4:5]
	s_branch .Lgb2_acq

.Lgb2_spin:
	s_sleep 1
	global_load_dword v7, v6, s[4:5] sc1
	s_add_i32 s12, s12, 1
	s_waitcnt vmcnt(0)
	v_readfirstlane_b32 s13, v7
	s_cmp_lg_u32 s13, 2
	s_cbranch_scc1 .Lgb2_acq
	s_cmp_lt_u32 s12, 0x10000
	s_cbranch_scc1 .Lgb2_spin
.Lgb2_acq:
	buffer_inv sc1
.LBB0_388:
	s_or_b64 exec, exec, s[0:1]
	s_add_u32 s52, s74, 0x18800000
	v_mov_b32_e32 v10, v214
	s_waitcnt lgkmcnt(0)
	v_cndmask_b32_e64 v0, 0, 1, s[8:9]
	s_barrier
	s_addc_u32 s53, s75, 0
	v_cmp_ne_u32_e64 s[78:79], 1, v0
	s_andn2_b64 vcc, exec, s[8:9]
	v_readfirstlane_b32 s5, v10
	s_cbranch_vccnz .LBB0_406
	v_lshlrev_b32_e32 v0, 4, v10
	v_add_u32_e32 v2, 0x2000, v0
	v_ashrrev_i32_e32 v1, 31, v2
	v_lshrrev_b32_e32 v1, 22, v1
	v_add_u32_e32 v1, v2, v1
	v_ashrrev_i32_e32 v1, 10, v1
	v_mul_i32_i24_e32 v3, 0x400, v1
	v_sub_u32_e32 v2, v2, v3
	v_lshrrev_b32_e32 v3, 4, v2
	v_bitop3_b32 v2, v3, v2, 32 bitop3:0x6c
	v_ashrrev_i32_e32 v3, 31, v2
	v_lshrrev_b32_e32 v3, 26, v3
	v_add_u32_e32 v3, v2, v3
	v_lshlrev_b32_e32 v4, 3, v1
	v_ashrrev_i32_e32 v11, 6, v3
	v_and_b32_e32 v4, -16, v4
	v_add_u32_e32 v4, v11, v4
	v_and_b32_e32 v5, 3, v11
	s_mov_b32 s0, 0x1fffe0
	v_lshrrev_b32_e32 v6, 2, v4
	v_lshlrev_b32_e32 v7, 1, v4
	v_and_b32_e32 v3, 0xc0, v3
	v_and_or_b32 v5, v4, s0, v5
	v_and_b32_e32 v6, 4, v6
	v_and_b32_e32 v7, 24, v7
	v_sub_u32_e32 v2, v2, v3
	v_mov_b32_e32 v3, 1
	v_or3_b32 v5, v5, v6, v7
	v_lshlrev_b32_e32 v6, 5, v1
	v_ashrrev_i16_sdwa v2, v3, sext(v2) dst_sel:DWORD dst_unused:UNUSED_PAD src0_sel:DWORD src1_sel:BYTE_0
	v_and_b32_e32 v6, 32, v6
	v_bfe_i32 v12, v2, 0, 16
	v_add_lshl_u32 v2, v6, v12, 1
	v_lshl_add_u32 v152, v5, 11, v2
	v_lshl_add_u32 v154, v4, 11, v2
	v_bfe_i32 v2, v10, 27, 1
	v_lshrrev_b32_e32 v2, 22, v2
	v_add_u32_e32 v2, v0, v2
	v_and_b32_e32 v2, 0xfffffc00, v2
	v_sub_u32_e32 v0, v0, v2
	v_lshrrev_b32_e32 v2, 4, v0
	v_ashrrev_i32_e32 v4, 31, v10
	v_bitop3_b32 v0, v2, v0, 32 bitop3:0x6c
	v_lshrrev_b32_e32 v4, 26, v4
	v_ashrrev_i32_e32 v2, 31, v0
	v_add_u32_e32 v4, v10, v4
	v_lshrrev_b32_e32 v2, 26, v2
	v_ashrrev_i32_e32 v14, 6, v4
	v_add_u32_e32 v2, v0, v2
	v_lshlrev_b32_e32 v4, 3, v14
	s_add_u32 s3, s74, 0x800000
	v_ashrrev_i32_e32 v13, 6, v2
	v_and_b32_e32 v4, -16, v4
	s_addc_u32 s30, s75, 0
	v_add_u32_e32 v4, v13, v4
	v_and_b32_e32 v5, 3, v13
	s_ashr_i32 s34, s2, 31
	v_and_or_b32 v5, v4, s0, v5
	s_lshr_b32 s0, s34, 29
	s_add_i32 s0, s2, s0
	s_ashr_i32 s8, s5, 6
	s_ashr_i32 s1, s0, 3
	s_and_b32 s0, s0, -8
	s_ashr_i32 s9, s5, 8
	s_lshl_b32 s31, s8, 10
	s_sub_i32 s0, s2, s0
	s_cmp_lt_i32 s0, 0
	s_movk_i32 s35, 0x61
	s_cselect_b32 s4, s35, 0x60
	s_mul_i32 s0, s0, s4
	s_add_i32 s0, s0, s1
	s_ashr_i32 s1, s0, 31
	s_lshr_b32 s1, s1, 27
	s_add_i32 s1, s0, s1
	s_ashr_i32 s4, s1, 5
	s_andn2_b32 s1, s1, 31
	s_sub_i32 s0, s0, s1
	s_bfe_i32 s1, s0, 0x80000
	s_bfe_u32 s1, s1, 0x3000c
	s_add_i32 s1, s0, s1
	s_lshl_b32 s6, s4, 3
	s_bfe_i32 s4, s1, 0x80000
	s_and_b32 s1, s1, 0xf8
	s_sub_i32 s0, s0, s1
	s_sext_i32_i8 s0, s0
	s_sext_i32_i16 s4, s4
	s_add_i32 s20, s6, s0
	v_lshrrev_b32_e32 v6, 2, v4
	v_lshlrev_b32_e32 v7, 1, v4
	v_and_b32_e32 v2, 0xc0, v2
	s_lshr_b32 s4, s4, 3
	s_lshl_b32 s0, s20, 8
	v_and_b32_e32 v6, 4, v6
	v_and_b32_e32 v7, 24, v7
	v_sub_u32_e32 v0, v0, v2
	s_ashr_i32 s1, s0, 31
	s_bfe_i64 s[6:7], s[4:5], 0x100000
	v_or3_b32 v5, v5, v6, v7
	v_lshlrev_b32_e32 v6, 5, v14
	v_ashrrev_i16_sdwa v0, v3, sext(v0) dst_sel:DWORD dst_unused:UNUSED_PAD src0_sel:DWORD src1_sel:BYTE_0
	s_lshl_b64 s[0:1], s[0:1], 11
	s_lshl_b64 s[6:7], s[6:7], 19
	v_and_b32_e32 v6, 32, v6
	v_bfe_i32 v15, v0, 0, 16
	s_add_u32 s6, s3, s6
	v_add_lshl_u32 v0, v6, v15, 1
	s_addc_u32 s7, s30, s7
	s_add_i32 s36, s31, 0
	v_lshl_add_u32 v156, v5, 11, v0
	s_add_i32 m0, s36, 0x10000
	v_lshl_add_u32 v158, v4, 11, v0
	global_load_lds_dwordx4 v156, s[6:7]
	s_add_i32 m0, s36, 0x12000
	s_add_u32 s10, s6, 0x40000
	global_load_lds_dwordx4 v152, s[6:7]
	s_addc_u32 s11, s7, 0
	s_add_i32 m0, s36, 0x14000
	v_mov_b32_e32 v0, 0
	global_load_lds_dwordx4 v156, s[10:11]
	s_add_i32 m0, s36, 0x16000
	s_add_u32 s26, s52, s0
	s_addc_u32 s27, s53, s1
	s_add_i32 s37, s36, 0x2000
	global_load_lds_dwordx4 v152, s[10:11]
	s_mov_b32 m0, s36
	s_add_u32 s0, s26, 0x40000
	global_load_lds_dwordx4 v158, s[26:27]
	s_mov_b32 m0, s37
	s_addc_u32 s1, s27, 0
	s_add_i32 s38, s36, 0x4000
	global_load_lds_dwordx4 v154, s[26:27]
	s_mov_b32 m0, s38
	s_add_i32 s39, s36, 0x6000
	global_load_lds_dwordx4 v158, s[0:1]
	s_mov_b32 m0, s39
	v_mov_b32_e32 v157, v0
	global_load_lds_dwordx4 v154, s[0:1]
	v_mov_b32_e32 v153, v0
	v_mov_b32_e32 v159, v0
	v_mov_b32_e32 v155, v0
	s_cmp_eq_u32 s9, 1
	s_mov_b32 s40, 0
	v_lshl_add_u64 v[8:9], s[6:7], 0, v[156:157]
	v_lshl_add_u64 v[6:7], s[6:7], 0, v[152:153]
	v_lshl_add_u64 v[2:3], s[26:27], 0, v[158:159]
	s_cselect_b64 s[0:1], -1, 0
	s_cmp_lg_u32 s9, 1
	v_lshl_add_u64 v[4:5], s[26:27], 0, v[154:155]
	s_cbranch_scc1 .LBB0_391
	s_barrier

.LBB0_406:
	s_waitcnt vmcnt(0)
	s_barrier
	s_and_saveexec_b64 s[0:1], s[70:71]
	s_cbranch_execz .LBB0_458
	v_mov_b32_e32 v0, 0x27d60
	ds_read_b32 v1, v0
	ds_read_b32 v2, v0 offset:4
	v_readlane_b32 s3, v244, 30
	s_add_u32 s4, s74, 0x4000
	s_addc_u32 s5, s75, 0
	v_mov_b32_e32 v4, 1
	s_lshl_b32 s3, s3, 8
	s_add_i32 s3, s3, 0x1400
	v_mov_b32_e32 v3, s3
	v_mov_b32_e32 v6, 0x3500
	s_waitcnt lgkmcnt(0)
	global_atomic_add v5, v3, v4, s[4:5] sc0
	v_readfirstlane_b32 s6, v1
	v_readfirstlane_b32 s7, v2
	s_mul_i32 s11, s6, 4
	s_waitcnt vmcnt(0)
	v_readfirstlane_b32 s10, v5
	s_add_i32 s10, s10, 1
	s_cmp_lg_u32 s10, s11
	s_cbranch_scc1 .Lgb3_poll
	buffer_wbl2 sc1
	s_waitcnt vmcnt(0)
	v_mov_b32_e32 v3, 0x3400
	global_atomic_add v5, v3, v4, s[4:5] sc0
	s_mul_i32 s11, s7, 4
	s_waitcnt vmcnt(0)
	v_readfirstlane_b32 s10, v5
	s_add_i32 s10, s10, 1
	s_cmp_lg_u32 s10, s11
	s_cbranch_scc1 .Lgb3_poll
	global_atomic_add v6, v4, s[4:5]
	s_branch .Lgb3_acq

.Lgb3_spin:
	s_sleep 1
	global_load_dword v7, v6, s[4:5] sc1
	s_add_i32 s12, s12, 1
	s_waitcnt vmcnt(0)
	v_readfirstlane_b32 s13, v7
	s_cmp_lg_u32 s13, 3
	s_cbranch_scc1 .Lgb3_acq
	s_cmp_lt_u32 s12, 0x10000
	s_cbranch_scc1 .Lgb3_spin
.Lgb3_acq:
	buffer_inv sc1
.LBB0_458:
	s_or_b64 exec, exec, s[0:1]
	v_readlane_b32 s0, v244, 22
	v_readlane_b32 s1, v244, 23
	s_waitcnt lgkmcnt(0)
	v_mov_b32_e32 v0, v214
	s_andn2_b64 vcc, exec, s[0:1]
	v_cndmask_b32_e64 v1, 0, 1, s[0:1]
	v_cmp_ne_u32_e64 s[80:81], 1, v1
	s_barrier
	s_cbranch_vccnz .LBB0_469
	v_and_b32_e32 v1, 63, v214
	v_lshlrev_b32_e32 v2, 3, v1
	v_lshlrev_b32_e32 v5, 4, v1
	v_add_u32_e32 v3, 0x2000000, v2
	v_add_u32_e32 v4, 0x18800000, v2
	v_add_u32_e32 v2, 0x8000000, v2
	v_mov_b32_e32 v6, 0x1f00000
	v_mov_b32_e32 v143, 0x358637bd
	global_load_dwordx4 v[80:83], v5, s[22:23] offset:0
	global_load_dwordx4 v[84:87], v5, s[22:23] offset:1024
	global_load_dwordx4 v[88:91], v5, s[22:23] offset:2048
	global_load_dwordx4 v[92:95], v5, s[22:23] offset:3072
	s_lshl_b32 s5, s66, 3
	s_mov_b32 s35, s68

.LBB0_469:
	s_waitcnt vmcnt(0)
	s_waitcnt lgkmcnt(0)
	s_barrier
	s_and_saveexec_b64 s[0:1], s[70:71]
	s_cbranch_execz .LBB0_521
	v_mov_b32_e32 v0, 0x27d60
	ds_read_b32 v1, v0
	ds_read_b32 v2, v0 offset:4
	v_readlane_b32 s3, v244, 30
	s_add_u32 s4, s74, 0x4000
	s_addc_u32 s5, s75, 0
	v_mov_b32_e32 v4, 1
	s_lshl_b32 s3, s3, 8
	s_add_i32 s3, s3, 0x1400
	v_mov_b32_e32 v3, s3
	v_mov_b32_e32 v6, 0x3500
	s_waitcnt lgkmcnt(0)
	global_atomic_add v5, v3, v4, s[4:5] sc0
	v_readfirstlane_b32 s6, v1
	v_readfirstlane_b32 s7, v2
	s_mul_i32 s11, s6, 5
	s_waitcnt vmcnt(0)
	v_readfirstlane_b32 s10, v5
	s_add_i32 s10, s10, 1
	s_cmp_lg_u32 s10, s11
	s_cbranch_scc1 .Lgb4_poll
	buffer_wbl2 sc1
	s_waitcnt vmcnt(0)
	v_mov_b32_e32 v3, 0x3400
	global_atomic_add v5, v3, v4, s[4:5] sc0
	s_mul_i32 s11, s7, 5
	s_waitcnt vmcnt(0)
	v_readfirstlane_b32 s10, v5
	s_add_i32 s10, s10, 1
	s_cmp_lg_u32 s10, s11
	s_cbranch_scc1 .Lgb4_poll
	global_atomic_add v6, v4, s[4:5]
	s_branch .Lgb4_acq

.Lgb4_spin:
	s_sleep 1
	global_load_dword v7, v6, s[4:5] sc1
	s_add_i32 s12, s12, 1
	s_waitcnt vmcnt(0)
	v_readfirstlane_b32 s13, v7
	s_cmp_lg_u32 s13, 4
	s_cbranch_scc1 .Lgb4_acq
	s_cmp_lt_u32 s12, 0x10000
	s_cbranch_scc1 .Lgb4_spin
.Lgb4_acq:
	buffer_inv sc1
.LBB0_521:
	s_or_b64 exec, exec, s[0:1]
	v_mov_b32_e32 v12, v214
	s_cmpk_lt_i32 s2, 0x10ac
	s_waitcnt lgkmcnt(0)
	s_barrier
	s_cselect_b64 s[0:1], -1, 0
	s_cmpk_gt_i32 s2, 0x10ab
	v_readfirstlane_b32 s6, v12
	s_cbranch_scc1 .LBB0_527
	s_ashr_i32 s3, s2, 31
	s_lshr_b32 s3, s3, 29
	s_add_i32 s3, s2, s3
	s_and_b32 s4, s3, -8
	s_sub_i32 s7, s2, s4
	s_cmp_gt_i32 s7, 3
	s_cbranch_scc0 .LBB0_524
	s_mul_i32 s4, s7, 0x215
	s_add_i32 s8, s4, 4
	s_cbranch_execz .LBB0_525
	s_branch .LBB0_526

.LBB0_629:
	s_waitcnt vmcnt(0)
	s_waitcnt lgkmcnt(0)
	s_barrier
	s_and_saveexec_b64 s[0:1], s[70:71]
	s_cbranch_execz .LBB0_681
	v_mov_b32_e32 v0, 0x27d60
	ds_read_b32 v1, v0
	ds_read_b32 v2, v0 offset:4
	v_readlane_b32 s3, v244, 30
	s_add_u32 s4, s74, 0x4000
	s_addc_u32 s5, s75, 0
	v_mov_b32_e32 v4, 1
	s_lshl_b32 s3, s3, 8
	s_add_i32 s3, s3, 0x1400
	v_mov_b32_e32 v3, s3
	v_mov_b32_e32 v6, 0x3500
	s_waitcnt lgkmcnt(0)
	global_atomic_add v5, v3, v4, s[4:5] sc0
	v_readfirstlane_b32 s6, v1
	v_readfirstlane_b32 s7, v2
	s_mul_i32 s11, s6, 6
	s_waitcnt vmcnt(0)
	v_readfirstlane_b32 s10, v5
	s_add_i32 s10, s10, 1
	s_cmp_lg_u32 s10, s11
	s_cbranch_scc1 .Lgb5_poll
	buffer_wbl2 sc1
	s_waitcnt vmcnt(0)
	v_mov_b32_e32 v3, 0x3400
	global_atomic_add v5, v3, v4, s[4:5] sc0
	s_mul_i32 s11, s7, 6
	s_waitcnt vmcnt(0)
	v_readfirstlane_b32 s10, v5
	s_add_i32 s10, s10, 1
	s_cmp_lg_u32 s10, s11
	s_cbranch_scc1 .Lgb5_poll
	global_atomic_add v6, v4, s[4:5]
	s_branch .Lgb5_acq

.Lgb5_spin:
	s_sleep 1
	global_load_dword v7, v6, s[4:5] sc1
	s_add_i32 s12, s12, 1
	s_waitcnt vmcnt(0)
	v_readfirstlane_b32 s13, v7
	s_cmp_lg_u32 s13, 5
	s_cbranch_scc1 .Lgb5_acq
	s_cmp_lt_u32 s12, 0x10000
	s_cbranch_scc1 .Lgb5_spin
.Lgb5_acq:
	buffer_inv sc1
.LBB0_681:
	s_or_b64 exec, exec, s[0:1]
	v_mov_b32_e32 v9, v214
	s_waitcnt lgkmcnt(0)
	s_barrier
	s_and_b64 vcc, exec, s[78:79]
	v_readfirstlane_b32 s0, v9
	s_cbranch_vccnz .LBB0_701
	v_lshlrev_b32_e32 v0, 4, v9
	v_add_u32_e32 v1, 0x2000, v0
	v_ashrrev_i32_e32 v2, 31, v1
	v_lshrrev_b32_e32 v2, 22, v2
	v_add_u32_e32 v2, v1, v2
	v_ashrrev_i32_e32 v8, 10, v2
	v_mul_i32_i24_e32 v2, 0x400, v8
	v_sub_u32_e32 v1, v1, v2
	v_lshrrev_b32_e32 v2, 4, v1
	v_bitop3_b32 v1, v2, v1, 32 bitop3:0x6c
	v_ashrrev_i32_e32 v2, 31, v1
	v_lshrrev_b32_e32 v2, 26, v2
	v_add_u32_e32 v2, v1, v2
	v_lshlrev_b32_e32 v3, 3, v8
	v_ashrrev_i32_e32 v10, 6, v2
	v_and_b32_e32 v3, -16, v3
	v_add_u32_e32 v3, v10, v3
	v_and_b32_e32 v4, 3, v10
	s_mov_b32 s4, 0xffffe0
	v_lshrrev_b32_e32 v5, 2, v3
	v_lshlrev_b32_e32 v6, 1, v3
	v_and_b32_e32 v2, 0xc0, v2
	v_and_or_b32 v4, v3, s4, v4
	v_and_b32_e32 v5, 4, v5
	v_and_b32_e32 v6, 24, v6
	v_sub_u32_e32 v1, v1, v2
	v_mov_b32_e32 v2, 1
	v_or3_b32 v4, v4, v5, v6
	v_lshlrev_b32_e32 v5, 5, v8
	v_ashrrev_i16_sdwa v1, v2, sext(v1) dst_sel:DWORD dst_unused:UNUSED_PAD src0_sel:DWORD src1_sel:BYTE_0
	s_movk_i32 s6, 0xb00
	v_and_b32_e32 v11, 32, v5
	v_bfe_i32 v12, v1, 0, 16
	v_mul_u32_u24_e32 v4, 0xb00, v4
	v_add_u32_e32 v1, v11, v12
	v_mul_lo_u32 v3, v3, s6
	v_add_lshl_u32 v128, v4, v1, 1
	v_add_lshl_u32 v130, v1, v3, 1
	v_bfe_i32 v1, v9, 27, 1
	v_lshrrev_b32_e32 v1, 22, v1
	v_add_u32_e32 v1, v0, v1
	v_and_b32_e32 v1, 0xfffffc00, v1
	v_sub_u32_e32 v0, v0, v1
	v_lshrrev_b32_e32 v1, 4, v0
	v_ashrrev_i32_e32 v3, 31, v9
	v_bitop3_b32 v0, v1, v0, 32 bitop3:0x6c
	v_lshrrev_b32_e32 v3, 26, v3
	v_ashrrev_i32_e32 v1, 31, v0
	v_add_u32_e32 v3, v9, v3
	v_lshrrev_b32_e32 v1, 26, v1
	v_ashrrev_i32_e32 v14, 6, v3
	v_add_u32_e32 v1, v0, v1
	v_lshlrev_b32_e32 v3, 3, v14
	s_add_u32 s3, s74, 0x1500000
	v_ashrrev_i32_e32 v13, 6, v1
	v_and_b32_e32 v3, -16, v3
	s_addc_u32 s30, s75, 0
	v_add_u32_e32 v3, v13, v3
	v_and_b32_e32 v4, 3, v13
	s_ashr_i32 s34, s2, 31
	v_and_or_b32 v4, v3, s4, v4
	s_lshr_b32 s4, s34, 29
	s_add_i32 s4, s2, s4
	s_ashr_i32 s7, s0, 6
	s_ashr_i32 s5, s4, 3
	s_and_b32 s4, s4, -8
	s_ashr_i32 s1, s0, 8
	s_lshl_b32 s31, s7, 10
	s_sub_i32 s4, s2, s4
	s_cmp_lt_i32 s4, 0
	s_movk_i32 s35, 0x61
	s_cselect_b32 s8, s35, 0x60
	s_mul_i32 s4, s4, s8
	s_add_i32 s4, s4, s5
	s_ashr_i32 s5, s4, 31
	s_lshr_b32 s5, s5, 27
	s_add_i32 s5, s4, s5
	s_ashr_i32 s8, s5, 5
	s_and_b32 s5, s5, 0xffe0
	s_sub_i32 s4, s4, s5
	s_bfe_i32 s5, s4, 0x80000
	s_bfe_u32 s5, s5, 0x3000c
	s_add_i32 s5, s4, s5
	s_bfe_i32 s9, s5, 0x80000
	s_and_b32 s5, s5, 0xf8
	s_sub_i32 s4, s4, s5
	s_lshl_b32 s8, s8, 3
	s_sext_i32_i8 s4, s4
	s_add_i32 s59, s8, s4
	v_lshrrev_b32_e32 v5, 2, v3
	v_lshlrev_b32_e32 v6, 1, v3
	v_and_b32_e32 v1, 0xc0, v1
	s_sext_i32_i16 s9, s9
	s_lshl_b32 s4, s59, 8
	v_and_b32_e32 v5, 4, v5
	v_and_b32_e32 v6, 24, v6
	v_sub_u32_e32 v0, v0, v1
	s_mul_hi_i32 s11, s4, 0x1600
	s_ashr_i32 s4, s9, 3
	v_or3_b32 v4, v4, v5, v6
	v_lshlrev_b32_e32 v5, 5, v14
	v_ashrrev_i16_sdwa v0, v2, sext(v0) dst_sel:DWORD dst_unused:UNUSED_PAD src0_sel:DWORD src1_sel:BYTE_0
	s_lshr_b32 s10, s9, 3
	s_mul_hi_i32 s5, s4, 0x160000
	s_mul_i32 s4, s4, 0x160000
	v_and_b32_e32 v15, 32, v5
	v_bfe_i32 v16, v0, 0, 16
	s_add_u32 s24, s3, s4
	v_mul_u32_u24_e32 v4, 0xb00, v4
	v_add_u32_e32 v0, v15, v16
	s_addc_u32 s25, s30, s5
	s_add_i32 s36, s31, 0
	v_add_lshl_u32 v132, v4, v0, 1
	s_add_i32 m0, s36, 0x10000
	s_mul_i32 s8, s59, 0x160000
	global_load_lds_dwordx4 v132, s[24:25]
	s_add_i32 m0, s36, 0x12000
	s_add_u32 s4, s24, 0xb0000
	global_load_lds_dwordx4 v128, s[24:25]
	s_addc_u32 s5, s25, 0
	s_add_i32 m0, s36, 0x14000
	v_mul_lo_u32 v1, v3, s6
	global_load_lds_dwordx4 v132, s[4:5]
	s_add_i32 m0, s36, 0x16000
	v_add_lshl_u32 v134, v0, v1, 1
	global_load_lds_dwordx4 v128, s[4:5]
	v_readlane_b32 s4, v244, 24
	v_readlane_b32 s5, v244, 25
	s_add_u32 s22, s4, s8
	s_addc_u32 s23, s5, s11
	s_add_i32 s37, s36, 0x2000
	s_mov_b32 m0, s36
	s_add_u32 s4, s22, 0xb0000
	global_load_lds_dwordx4 v134, s[22:23]
	s_mov_b32 m0, s37
	s_addc_u32 s5, s23, 0
	s_add_i32 s38, s36, 0x4000
	global_load_lds_dwordx4 v130, s[22:23]
	s_mov_b32 m0, s38
	s_add_i32 s39, s36, 0x6000
	global_load_lds_dwordx4 v134, s[4:5]
	s_mov_b32 m0, s39
	v_mov_b32_e32 v133, 0
	global_load_lds_dwordx4 v130, s[4:5]
	v_mov_b32_e32 v129, v133
	v_mov_b32_e32 v135, v133
	v_mov_b32_e32 v131, v133
	s_cmp_eq_u32 s1, 1
	s_mov_b32 s40, 0
	v_lshl_add_u64 v[6:7], s[24:25], 0, v[132:133]
	v_lshl_add_u64 v[4:5], s[24:25], 0, v[128:129]
	v_lshl_add_u64 v[0:1], s[22:23], 0, v[134:135]
	s_cselect_b64 s[4:5], -1, 0
	s_cmp_lg_u32 s1, 1
	v_lshl_add_u64 v[2:3], s[22:23], 0, v[130:131]
	s_cbranch_scc1 .LBB0_684
	s_barrier

.LBB0_701:
	s_waitcnt vmcnt(0)
	s_waitcnt vmcnt(0)
	s_barrier
	s_and_saveexec_b64 s[0:1], s[70:71]
	s_cbranch_execz .LBB0_753
	v_mov_b32_e32 v0, 0x27d60
	ds_read_b32 v1, v0
	ds_read_b32 v2, v0 offset:4
	v_readlane_b32 s3, v244, 30
	s_add_u32 s4, s74, 0x4000
	s_addc_u32 s5, s75, 0
	v_mov_b32_e32 v4, 1
	s_lshl_b32 s3, s3, 8
	s_add_i32 s3, s3, 0x1400
	v_mov_b32_e32 v3, s3
	v_mov_b32_e32 v6, 0x3500
	s_waitcnt lgkmcnt(0)
	global_atomic_add v5, v3, v4, s[4:5] sc0
	v_readfirstlane_b32 s6, v1
	v_readfirstlane_b32 s7, v2
	s_mul_i32 s11, s6, 7
	s_waitcnt vmcnt(0)
	v_readfirstlane_b32 s10, v5
	s_add_i32 s10, s10, 1
	s_cmp_lg_u32 s10, s11
	s_cbranch_scc1 .Lgb6_poll
	buffer_wbl2 sc1
	s_waitcnt vmcnt(0)
	v_mov_b32_e32 v3, 0x3400
	global_atomic_add v5, v3, v4, s[4:5] sc0
	s_mul_i32 s11, s7, 7
	s_waitcnt vmcnt(0)
	v_readfirstlane_b32 s10, v5
	s_add_i32 s10, s10, 1
	s_cmp_lg_u32 s10, s11
	s_cbranch_scc1 .Lgb6_poll
	global_atomic_add v6, v4, s[4:5]
	s_branch .Lgb6_acq

.Lgb6_spin:
	s_sleep 1
	global_load_dword v7, v6, s[4:5] sc1
	s_add_i32 s12, s12, 1
	s_waitcnt vmcnt(0)
	v_readfirstlane_b32 s13, v7
	s_cmp_lg_u32 s13, 6
	s_cbranch_scc1 .Lgb6_acq
	s_cmp_lt_u32 s12, 0x10000
	s_cbranch_scc1 .Lgb6_spin
.Lgb6_acq:
	buffer_inv sc1
.LBB0_753:
	s_or_b64 exec, exec, s[0:1]
	s_and_b64 vcc, exec, s[80:81]
	s_waitcnt lgkmcnt(0)
	s_barrier
	s_cbranch_vccnz .LBB0_756
	v_and_b32_e32 v1, 63, v214
	v_readlane_b32 s22, v244, 10
	v_readlane_b32 s23, v244, 11
	v_lshlrev_b32_e32 v2, 3, v1
	v_lshlrev_b32_e32 v5, 4, v1
	v_add_u32_e32 v3, 0x16800000, v2
	v_mov_b32_e32 v4, v5
	v_mov_b32_e32 v143, 0x358637bd
	s_nop 2
	global_load_dwordx4 v[80:83], v5, s[22:23] offset:0
	global_load_dwordx4 v[84:87], v5, s[22:23] offset:1024
	global_load_dwordx4 v[88:91], v5, s[22:23] offset:2048
	global_load_dwordx4 v[92:95], v5, s[22:23] offset:3072
	s_lshl_b32 s5, s66, 3
	s_mov_b32 s35, s68
